# baseline (speedup 1.0000x reference)
; __device__ __forceinline__ unsigned cvt_pk_bf16(float lo, float hi) { unsigned r; asm volatile("v_cvt_pk_bf16_f32 %0, %1, %2" : "=v"(r) : "v"(lo), "v"(hi)); return r; }
; __device__ __forceinline__ float bf_lo(unsigned w) { return __uint_as_float(w << 16); }
; __device__ __forceinline__ float bf_hi(unsigned w) { return __uint_as_float(w & 0xffff0000u); }
; __device__ __forceinline__ void retc3_compute(LAS unsigned char* lds, const bf16_t* proj, bf16_t* outb, int out_ld, const float* cgn, float lg, int h, int n, int tid) {
;     ...
;     u32x2 gr[8];
; #pragma unroll
;     for (int et = 0; et < 8; ++et) gr[et] = *(const u32x2*)(rowp + C_CG + h * 128 + 16 * et + quad * 4);
;     float ms = 0.f;
; #pragma unroll
;     for (int et = 0; et < 8; ++et) ms += (acc[et][0] * acc[et][0] + acc[et][1] * acc[et][1]) + (acc[et][2] * acc[et][2] + acc[et][3] * acc[et][3]);
;     ms += __shfl_xor(ms, 16); ms += __shfl_xor(ms, 32);
;     const float rs = __builtin_amdgcn_rsqf(ms * (1.0f / 128.0f) + EPS);
; #pragma unroll
;     for (int et = 0; et < 8; ++et) { const int e = 16 * et + quad * 4;
;         const f32x4 gn = *(const f32x4*)(cgn + h * 128 + e);
;         const float gz[4] = {bf_lo(gr[et].x), bf_hi(gr[et].x), bf_lo(gr[et].y), bf_hi(gr[et].y)}; float o[4];
; #pragma unroll
;         for (int j = 0; j < 4; ++j) { const float sl = gz[j] * __builtin_amdgcn_rcpf(1.0f + __expf(-gz[j])); o[j] = sl * (acc[et][j] * rs * gn[j]); }
;         u32x2 wv; wv.x = cvt_pk_bf16(o[0], o[1]); wv.y = cvt_pk_bf16(o[2], o[3]); *(u32x2*)(orow + h * 128 + e) = wv; }
.LBB0_382:
	s_or_b64 exec, exec, vcc
	v_lshl_add_u32 v131, s43, 7, v148
	v_mov_b64_e32 v[98:99], s[24:25]
	v_mad_i64_i32 v[98:99], s[44:45], v131, s23, v[98:99]
	s_and_b32 s44, s42, 0xffffff80
	s_ashr_i32 s45, s44, 31
	s_lshl_b64 s[42:43], s[44:45], 1
	v_lshl_add_u64 v[98:99], v[98:99], 0, s[42:43]
	v_mov_b32_e32 v133, v32
	v_lshl_add_u64 v[98:99], v[98:99], 0, v[132:133]
	s_mov_b64 vcc, 0x3f00
	v_lshl_add_u64 v[110:111], v[98:99], 0, vcc
	v_add_co_u32_e32 v98, vcc, 0x3000, v98
	v_lshl_add_u64 v[100:101], s[44:45], 2, v[128:129]
	s_nop 0
	v_addc_co_u32_e32 v99, vcc, 0, v99, vcc
	global_load_dwordx4 v[236:239], v[100:101], off offset:128
	global_load_dwordx4 v[240:243], v[100:101], off offset:192
	global_load_dwordx4 v[244:247], v[100:101], off offset:256
	global_load_dwordx4 v[248:251], v[100:101], off offset:320
	global_load_dwordx2 v[112:113], v[98:99], off offset:3840
	global_load_dwordx4 v[222:225], v[100:101], off
	v_pk_mul_f32 v[108:109], v[68:69], v[68:69]
	v_pk_mul_f32 v[164:165], v[72:73], v[72:73]
	v_pk_mul_f32 v[166:167], v[70:71], v[70:71]
	v_pk_mul_f32 v[226:227], v[66:67], v[66:67]
	v_pk_mul_f32 v[104:105], v[76:77], v[76:77]
	v_pk_mul_f32 v[106:107], v[74:75], v[74:75]
	v_mov_b32_e32 v228, v226
	v_mov_b32_e32 v229, v166
	v_mov_b32_e32 v166, v227
	v_mov_b32_e32 v226, v108
	v_mov_b32_e32 v227, v164
	v_mov_b32_e32 v164, v109
	v_pk_add_f32 v[108:109], v[226:227], v[164:165]
	v_pk_mov_b32 v[164:165], v[106:107], v[104:105] op_sel:[1,0]
	v_mov_b32_e32 v107, v105
	v_pk_add_f32 v[104:105], v[164:165], v[106:107]
	v_pk_add_f32 v[166:167], v[228:229], v[166:167]
	v_pk_add_f32 v[104:105], v[104:105], v[104:105] op_sel_hi:[0,1]
	v_mul_f32_e32 v104, v78, v78
	v_pk_add_f32 v[108:109], v[166:167], v[108:109]
	v_pk_fma_f32 v[106:107], v[78:79], v[78:79], v[104:105] op_sel_hi:[1,1,0]
	v_mul_f32_e32 v104, v80, v80
	v_pk_add_f32 v[108:109], v[108:109], v[108:109] op_sel_hi:[0,1]
	v_pk_fma_f32 v[164:165], v[80:81], v[80:81], v[104:105] op_sel_hi:[1,1,0]
	v_mul_f32_e32 v106, v82, v82
	v_mul_f32_e32 v164, v83, v83
	v_mul_f32_e32 v104, v84, v84
	v_mul_f32_e32 v108, v85, v85
	v_pk_mul_f32 v[98:99], v[92:93], v[92:93]
	v_pk_mul_f32 v[102:103], v[90:91], v[90:91]
	v_pk_add_f32 v[106:107], v[106:107], v[164:165]
	v_pk_add_f32 v[104:105], v[104:105], v[108:109]
	v_readlane_b32 s20, v252, 11
	v_pk_add_f32 v[104:105], v[106:107], v[104:105]
	v_pk_mov_b32 v[106:107], v[102:103], v[98:99] op_sel:[1,0]
	v_mov_b32_e32 v103, v99
	v_pk_add_f32 v[98:99], v[106:107], v[102:103]
	v_pk_add_f32 v[104:105], v[104:105], v[104:105] op_sel_hi:[0,1]
	v_pk_add_f32 v[98:99], v[98:99], v[98:99] op_sel_hi:[0,1]
	v_mul_f32_e32 v98, v86, v86
	v_pk_fma_f32 v[102:103], v[86:87], v[86:87], v[98:99] op_sel_hi:[1,1,0]
	v_mul_f32_e32 v98, v88, v88
	v_pk_fma_f32 v[106:107], v[88:89], v[88:89], v[98:99] op_sel_hi:[1,1,0]
	v_mul_f32_e32 v102, v94, v94
	v_mul_f32_e32 v106, v95, v95
	v_mul_f32_e32 v98, v96, v96
	v_mul_f32_e32 v104, v97, v97
	v_pk_add_f32 v[102:103], v[102:103], v[106:107]
	v_pk_add_f32 v[98:99], v[98:99], v[104:105]
	global_load_dwordx2 v[164:165], v[110:111], off offset:32
	global_load_dwordx2 v[166:167], v[110:111], off offset:64
	global_load_dwordx2 v[108:109], v[110:111], off offset:96
	global_load_dwordx2 v[106:107], v[110:111], off offset:128
	v_pk_add_f32 v[98:99], v[102:103], v[98:99]
	v_and_b32_e32 v102, 64, v207
	v_add_f32_e32 v98, v98, v99
	v_xor_b32_e32 v99, 16, v207
	v_add_u32_e32 v102, 64, v102
	v_cmp_lt_i32_e32 vcc, v99, v102
	s_add_i32 s0, s0, s20
	s_waitcnt vmcnt(5)
	v_lshlrev_b32_e32 v230, 16, v113
	v_cndmask_b32_e32 v99, v207, v99, vcc
	v_lshlrev_b32_e32 v99, 2, v99
	ds_bpermute_b32 v99, v99, v98
	s_waitcnt vmcnt(4)
	v_mov_b32_e32 v235, v222
	v_and_b32_e32 v232, 0xffff0000, v113
	s_waitcnt lgkmcnt(0)
	v_add_f32_e32 v221, v98, v99
	v_xor_b32_e32 v98, 32, v207
	v_cmp_lt_i32_e32 vcc, v98, v102
	s_nop 1
	v_cndmask_b32_e32 v98, v207, v98, vcc
	v_lshlrev_b32_e32 v98, 2, v98
	ds_bpermute_b32 v228, v98, v221
	global_load_dwordx2 v[104:105], v[110:111], off offset:160
	global_load_dwordx2 v[102:103], v[110:111], off offset:192
	global_load_dwordx2 v[98:99], v[110:111], off offset:224
	v_mov_b64_e32 v[110:111], s[34:35]
	v_mad_i64_i32 v[226:227], s[44:45], v131, s23, v[110:111]
	s_waitcnt lgkmcnt(0)
	v_add_f32_e32 v110, v221, v228
	v_fmamk_f32 v110, v110, 0x3c000000, v204
	v_rsq_f32_e32 v110, v110
	v_lshlrev_b32_e32 v228, 16, v112
	v_and_b32_e32 v112, 0xffff0000, v112
	v_mul_f32_e32 v111, 0xbfb8aa3b, v228
	v_mul_f32_e32 v229, v66, v110
	v_mul_f32_e32 v66, 0xbfb8aa3b, v112
	v_exp_f32_e32 v66, v66
	v_mul_f32_e32 v113, v67, v110
	v_exp_f32_e32 v111, v111
	v_mul_f32_e32 v231, v68, v110
	v_add_f32_e32 v66, 1.0, v66
	v_rcp_f32_e32 v222, v66
	v_mul_f32_e32 v66, 0xbfb8aa3b, v230
	v_exp_f32_e32 v131, v66
	v_add_f32_e32 v111, 1.0, v111
	v_pk_mul_f32 v[66:67], v[222:223], v[112:113]
	v_rcp_f32_e32 v234, v111
	v_mul_f32_e32 v112, v66, v67
	v_mul_f32_e32 v67, 0xbfb8aa3b, v232
	v_exp_f32_e32 v113, v67
	v_add_f32_e32 v66, 1.0, v131
	v_rcp_f32_e32 v66, v66
	v_mov_b32_e32 v67, v224
	v_add_f32_e32 v68, 1.0, v113
	v_rcp_f32_e32 v224, v68
	v_pk_mul_f32 v[66:67], v[66:67], v[230:231]
	v_mul_f32_e32 v233, v69, v110
	v_mul_f32_e32 v113, v66, v67
	v_pk_mul_f32 v[66:67], v[224:225], v[232:233]
	v_lshl_add_u64 v[226:227], v[226:227], 0, s[42:43]
	v_pk_mul_f32 v[228:229], v[234:235], v[228:229]
	v_mul_f32_e32 v66, v66, v67
	v_mul_f32_e32 v111, v228, v229
	v_cvt_pk_bf16_f32 v68, v111, v112
	v_cvt_pk_bf16_f32 v69, v113, v66
	v_lshl_add_u64 v[66:67], v[226:227], 0, v[132:133]
	global_store_dwordx2 v[66:67], v[68:69], off
	global_load_dwordx4 v[222:225], v[100:101], off offset:64
	s_waitcnt vmcnt(8)
; __device__ __forceinline__ unsigned cvt_pk_bf16(float lo, float hi) { unsigned r; asm volatile("v_cvt_pk_bf16_f32 %0, %1, %2" : "=v"(r) : "v"(lo), "v"(hi)); return r; }
; __device__ __forceinline__ float bf_lo(unsigned w) { return __uint_as_float(w << 16); }
; __device__ __forceinline__ float bf_hi(unsigned w) { return __uint_as_float(w & 0xffff0000u); }
; __device__ __forceinline__ void retc3_compute(LAS unsigned char* lds, const bf16_t* proj, bf16_t* outb, int out_ld, const float* cgn, float lg, int h, int n, int tid) {
;     ...
;     for (int et = 0; et < 8; ++et) { const int e = 16 * et + quad * 4;
;         const f32x4 gn = *(const f32x4*)(cgn + h * 128 + e);
;         const float gz[4] = {bf_lo(gr[et].x), bf_hi(gr[et].x), bf_lo(gr[et].y), bf_hi(gr[et].y)}; float o[4];
; #pragma unroll
;         for (int j = 0; j < 4; ++j) { const float sl = gz[j] * __builtin_amdgcn_rcpf(1.0f + __expf(-gz[j])); o[j] = sl * (acc[et][j] * rs * gn[j]); }
;         u32x2 wv; wv.x = cvt_pk_bf16(o[0], o[1]); wv.y = cvt_pk_bf16(o[2], o[3]); *(u32x2*)(orow + h * 128 + e) = wv; }
	v_lshlrev_b32_e32 v68, 16, v164
	v_mul_f32_e32 v69, v70, v110
	v_mul_f32_e32 v113, v72, v110
	v_and_b32_e32 v70, 0xffff0000, v164
	v_and_b32_e32 v72, 0xffff0000, v165
	v_mul_f32_e32 v111, 0xbfb8aa3b, v68
	v_lshlrev_b32_e32 v112, 16, v165
	v_mul_f32_e32 v131, 0xbfb8aa3b, v70
	v_mul_f32_e32 v164, 0xbfb8aa3b, v72
	v_exp_f32_e32 v111, v111
	v_mul_f32_e32 v133, 0xbfb8aa3b, v112
	v_exp_f32_e32 v131, v131
	v_exp_f32_e32 v164, v164
	v_exp_f32_e32 v133, v133
	v_add_f32_e32 v111, 1.0, v111
	v_add_f32_e32 v131, 1.0, v131
	v_add_f32_e32 v221, 1.0, v164
	v_rcp_f32_e32 v164, v111
	v_add_f32_e32 v133, 1.0, v133
	v_rcp_f32_e32 v226, v133
	v_mul_f32_e32 v71, v71, v110
	v_mul_f32_e32 v73, v73, v110
	v_mul_f32_e32 v75, v75, v110
	v_mul_f32_e32 v77, v77, v110
	s_andn2_b64 vcc, exec, s[26:27]
	s_mov_b32 s42, s36
	s_waitcnt vmcnt(0)
	v_mov_b32_e32 v165, v222
	v_rcp_f32_e32 v222, v131
	v_mov_b32_e32 v227, v224
	v_rcp_f32_e32 v224, v221
	v_pk_mul_f32 v[68:69], v[164:165], v[68:69]
	v_pk_mul_f32 v[112:113], v[226:227], v[112:113]
	v_mul_f32_e32 v111, v68, v69
	v_pk_mul_f32 v[68:69], v[222:223], v[70:71]
	v_pk_mul_f32 v[70:71], v[224:225], v[72:73]
	v_mul_f32_e32 v68, v68, v69
	v_mul_f32_e32 v69, v70, v71
	v_mul_f32_e32 v112, v112, v113
	v_cvt_pk_bf16_f32 v68, v111, v68
	v_cvt_pk_bf16_f32 v69, v112, v69
	global_store_dwordx2 v[66:67], v[68:69], off offset:32
	v_lshlrev_b32_e32 v164, 16, v166
	v_and_b32_e32 v166, 0xffff0000, v166
	v_mul_f32_e32 v73, v74, v110
	v_lshlrev_b32_e32 v222, 16, v167
	v_and_b32_e32 v224, 0xffff0000, v167
	v_mul_f32_e32 v72, 0xbfb8aa3b, v164
	v_mul_f32_e32 v74, 0xbfb8aa3b, v166
	v_mul_f32_e32 v113, v76, v110
	v_mul_f32_e32 v76, 0xbfb8aa3b, v222
	v_mul_f32_e32 v111, 0xbfb8aa3b, v224
	v_exp_f32_e32 v72, v72
	v_exp_f32_e32 v74, v74
	v_exp_f32_e32 v76, v76
	v_exp_f32_e32 v111, v111
	v_add_f32_e32 v72, 1.0, v72
	v_add_f32_e32 v74, 1.0, v74
	v_add_f32_e32 v76, 1.0, v76
	v_add_f32_e32 v111, 1.0, v111
	v_rcp_f32_e32 v72, v72
	v_rcp_f32_e32 v74, v74
	v_rcp_f32_e32 v112, v76
	v_rcp_f32_e32 v76, v111
	v_mov_b32_e32 v165, v236
	v_mov_b32_e32 v167, v237
	v_mov_b32_e32 v223, v238
	v_mov_b32_e32 v225, v239
	v_pk_mul_f32 v[68:69], v[72:73], v[164:165]
	v_pk_mul_f32 v[70:71], v[74:75], v[166:167]
	v_pk_mul_f32 v[72:73], v[112:113], v[222:223]
	v_pk_mul_f32 v[74:75], v[76:77], v[224:225]
	v_mul_f32_e32 v68, v68, v69
	v_mul_f32_e32 v69, v70, v71
	v_mul_f32_e32 v70, v72, v73
	v_mul_f32_e32 v71, v74, v75
	v_cvt_pk_bf16_f32 v68, v68, v69
	v_cvt_pk_bf16_f32 v69, v70, v71
	global_store_dwordx2 v[66:67], v[68:69], off offset:64
	global_load_dwordx4 v[236:239], v[100:101], off offset:384
	v_mul_f32_e32 v77, v80, v110
	v_lshlrev_b32_e32 v80, 16, v108
	v_and_b32_e32 v108, 0xffff0000, v108
	v_lshlrev_b32_e32 v112, 16, v109
	v_and_b32_e32 v164, 0xffff0000, v109
	v_mul_f32_e32 v72, 0xbfb8aa3b, v80
	v_mul_f32_e32 v74, 0xbfb8aa3b, v108
	v_mul_f32_e32 v73, v78, v110
	v_mul_f32_e32 v76, 0xbfb8aa3b, v112
	v_mul_f32_e32 v78, 0xbfb8aa3b, v164
	v_exp_f32_e32 v72, v72
	v_exp_f32_e32 v74, v74
	v_exp_f32_e32 v76, v76
	v_exp_f32_e32 v78, v78
	v_add_f32_e32 v72, 1.0, v72
	v_add_f32_e32 v74, 1.0, v74
	v_add_f32_e32 v76, 1.0, v76
	v_add_f32_e32 v78, 1.0, v78
	v_rcp_f32_e32 v72, v72
	v_rcp_f32_e32 v74, v74
	v_rcp_f32_e32 v76, v76
	v_rcp_f32_e32 v78, v78
	v_mul_f32_e32 v75, v79, v110
	v_mul_f32_e32 v79, v81, v110
	v_mov_b32_e32 v81, v240
	v_mov_b32_e32 v109, v241
	v_mov_b32_e32 v113, v242
	v_mov_b32_e32 v165, v243
	v_pk_mul_f32 v[68:69], v[72:73], v[80:81]
	v_pk_mul_f32 v[70:71], v[74:75], v[108:109]
	v_pk_mul_f32 v[72:73], v[76:77], v[112:113]
	v_pk_mul_f32 v[74:75], v[78:79], v[164:165]
	v_mul_f32_e32 v68, v68, v69
	v_mul_f32_e32 v69, v70, v71
	v_mul_f32_e32 v70, v72, v73
	v_mul_f32_e32 v71, v74, v75
	v_cvt_pk_bf16_f32 v68, v68, v69
	v_cvt_pk_bf16_f32 v69, v70, v71
	global_store_dwordx2 v[66:67], v[68:69], off offset:96
	global_load_dwordx4 v[240:243], v[100:101], off offset:448
	v_mul_f32_e32 v73, v82, v110
	v_lshlrev_b32_e32 v80, 16, v106
	v_and_b32_e32 v82, 0xffff0000, v106
	v_mul_f32_e32 v77, v84, v110
	v_lshlrev_b32_e32 v84, 16, v107
	v_and_b32_e32 v106, 0xffff0000, v107
	v_mul_f32_e32 v72, 0xbfb8aa3b, v80
	v_mul_f32_e32 v74, 0xbfb8aa3b, v82
	v_mul_f32_e32 v76, 0xbfb8aa3b, v84
	v_mul_f32_e32 v78, 0xbfb8aa3b, v106
	v_exp_f32_e32 v72, v72
	v_exp_f32_e32 v74, v74
	v_exp_f32_e32 v76, v76
	v_exp_f32_e32 v78, v78
	v_add_f32_e32 v72, 1.0, v72
	v_add_f32_e32 v74, 1.0, v74
	v_add_f32_e32 v76, 1.0, v76
; __device__ __forceinline__ unsigned cvt_pk_bf16(float lo, float hi) { unsigned r; asm volatile("v_cvt_pk_bf16_f32 %0, %1, %2" : "=v"(r) : "v"(lo), "v"(hi)); return r; }
; __device__ __forceinline__ float bf_lo(unsigned w) { return __uint_as_float(w << 16); }
; __device__ __forceinline__ float bf_hi(unsigned w) { return __uint_as_float(w & 0xffff0000u); }
; __device__ __forceinline__ void retc3_compute(LAS unsigned char* lds, const bf16_t* proj, bf16_t* outb, int out_ld, const float* cgn, float lg, int h, int n, int tid) {
;     ...
;     for (int et = 0; et < 8; ++et) { const int e = 16 * et + quad * 4;
;         const f32x4 gn = *(const f32x4*)(cgn + h * 128 + e);
;         const float gz[4] = {bf_lo(gr[et].x), bf_hi(gr[et].x), bf_lo(gr[et].y), bf_hi(gr[et].y)}; float o[4];
; #pragma unroll
;         for (int j = 0; j < 4; ++j) { const float sl = gz[j] * __builtin_amdgcn_rcpf(1.0f + __expf(-gz[j])); o[j] = sl * (acc[et][j] * rs * gn[j]); }
;         u32x2 wv; wv.x = cvt_pk_bf16(o[0], o[1]); wv.y = cvt_pk_bf16(o[2], o[3]); *(u32x2*)(orow + h * 128 + e) = wv; }
	v_add_f32_e32 v78, 1.0, v78
	v_rcp_f32_e32 v72, v72
	v_rcp_f32_e32 v74, v74
	v_rcp_f32_e32 v76, v76
	v_rcp_f32_e32 v78, v78
	v_mul_f32_e32 v75, v83, v110
	v_mul_f32_e32 v79, v85, v110
	v_mov_b32_e32 v81, v244
	v_mov_b32_e32 v83, v245
	v_mov_b32_e32 v85, v246
	v_mov_b32_e32 v107, v247
	v_pk_mul_f32 v[68:69], v[72:73], v[80:81]
	v_pk_mul_f32 v[70:71], v[74:75], v[82:83]
	v_pk_mul_f32 v[72:73], v[76:77], v[84:85]
	v_pk_mul_f32 v[74:75], v[78:79], v[106:107]
	v_mul_f32_e32 v68, v68, v69
	v_mul_f32_e32 v69, v70, v71
	v_mul_f32_e32 v70, v72, v73
	v_mul_f32_e32 v71, v74, v75
	v_cvt_pk_bf16_f32 v68, v68, v69
	v_cvt_pk_bf16_f32 v69, v70, v71
	global_store_dwordx2 v[66:67], v[68:69], off offset:128
	v_lshlrev_b32_e32 v80, 16, v104
	v_and_b32_e32 v82, 0xffff0000, v104
	v_mul_f32_e32 v73, v90, v110
	v_lshlrev_b32_e32 v84, 16, v105
	v_and_b32_e32 v90, 0xffff0000, v105
	v_mul_f32_e32 v72, 0xbfb8aa3b, v80
	v_mul_f32_e32 v74, 0xbfb8aa3b, v82
	v_mul_f32_e32 v76, 0xbfb8aa3b, v84
	v_mul_f32_e32 v78, 0xbfb8aa3b, v90
	v_exp_f32_e32 v72, v72
	v_exp_f32_e32 v74, v74
	v_exp_f32_e32 v76, v76
	v_exp_f32_e32 v78, v78
	v_add_f32_e32 v72, 1.0, v72
	v_add_f32_e32 v74, 1.0, v74
	v_add_f32_e32 v76, 1.0, v76
	v_add_f32_e32 v78, 1.0, v78
	v_rcp_f32_e32 v72, v72
	v_rcp_f32_e32 v74, v74
	v_rcp_f32_e32 v76, v76
	v_rcp_f32_e32 v78, v78
	v_mul_f32_e32 v75, v91, v110
	v_mul_f32_e32 v77, v92, v110
	v_mul_f32_e32 v79, v93, v110
	v_mov_b32_e32 v81, v248
	v_mov_b32_e32 v83, v249
	v_mov_b32_e32 v85, v250
	v_mov_b32_e32 v91, v251
	v_pk_mul_f32 v[68:69], v[72:73], v[80:81]
	v_pk_mul_f32 v[70:71], v[74:75], v[82:83]
	v_pk_mul_f32 v[72:73], v[76:77], v[84:85]
	v_pk_mul_f32 v[74:75], v[78:79], v[90:91]
	v_mul_f32_e32 v68, v68, v69
	v_mul_f32_e32 v69, v70, v71
	v_mul_f32_e32 v70, v72, v73
	v_mul_f32_e32 v71, v74, v75
	v_cvt_pk_bf16_f32 v68, v68, v69
	v_cvt_pk_bf16_f32 v69, v70, v71
	global_store_dwordx2 v[66:67], v[68:69], off offset:160
	v_lshlrev_b32_e32 v80, 16, v102
	v_and_b32_e32 v82, 0xffff0000, v102
	v_mul_f32_e32 v73, v86, v110
	v_lshlrev_b32_e32 v84, 16, v103
	v_and_b32_e32 v86, 0xffff0000, v103
	v_mul_f32_e32 v72, 0xbfb8aa3b, v80
	v_mul_f32_e32 v74, 0xbfb8aa3b, v82
	v_mul_f32_e32 v76, 0xbfb8aa3b, v84
	v_mul_f32_e32 v78, 0xbfb8aa3b, v86
	v_exp_f32_e32 v72, v72
	v_exp_f32_e32 v74, v74
	v_exp_f32_e32 v76, v76
	v_exp_f32_e32 v78, v78
	v_add_f32_e32 v72, 1.0, v72
	v_add_f32_e32 v74, 1.0, v74
	v_add_f32_e32 v76, 1.0, v76
	v_add_f32_e32 v78, 1.0, v78
	v_rcp_f32_e32 v72, v72
	v_rcp_f32_e32 v74, v74
	v_rcp_f32_e32 v76, v76
	v_rcp_f32_e32 v78, v78
	v_mul_f32_e32 v75, v87, v110
	v_mul_f32_e32 v77, v88, v110
	v_mul_f32_e32 v79, v89, v110
	s_waitcnt vmcnt(4)
	v_mov_b32_e32 v81, v236
	v_mov_b32_e32 v83, v237
	v_mov_b32_e32 v85, v238
	v_mov_b32_e32 v87, v239
	v_pk_mul_f32 v[68:69], v[72:73], v[80:81]
	v_pk_mul_f32 v[70:71], v[74:75], v[82:83]
	v_pk_mul_f32 v[72:73], v[76:77], v[84:85]
	v_pk_mul_f32 v[74:75], v[78:79], v[86:87]
	v_mul_f32_e32 v68, v68, v69
	v_mul_f32_e32 v69, v70, v71
	v_mul_f32_e32 v70, v72, v73
	v_mul_f32_e32 v71, v74, v75
	v_cvt_pk_bf16_f32 v68, v68, v69
	v_cvt_pk_bf16_f32 v69, v70, v71
	global_store_dwordx2 v[66:67], v[68:69], off offset:192
	v_lshlrev_b32_e32 v80, 16, v98
	v_and_b32_e32 v82, 0xffff0000, v98
	v_lshlrev_b32_e32 v84, 16, v99
	v_and_b32_e32 v86, 0xffff0000, v99
	v_mul_f32_e32 v72, 0xbfb8aa3b, v80
	v_mul_f32_e32 v74, 0xbfb8aa3b, v82
	v_mul_f32_e32 v76, 0xbfb8aa3b, v84
	v_mul_f32_e32 v78, 0xbfb8aa3b, v86
	v_exp_f32_e32 v72, v72
	v_exp_f32_e32 v74, v74
	v_exp_f32_e32 v76, v76
	v_exp_f32_e32 v78, v78
	v_add_f32_e32 v72, 1.0, v72
	v_add_f32_e32 v74, 1.0, v74
	v_add_f32_e32 v76, 1.0, v76
	v_add_f32_e32 v78, 1.0, v78
	v_rcp_f32_e32 v72, v72
	v_rcp_f32_e32 v74, v74
	v_rcp_f32_e32 v76, v76
	v_rcp_f32_e32 v78, v78
	v_mul_f32_e32 v73, v94, v110
	v_mul_f32_e32 v75, v95, v110
	v_mul_f32_e32 v77, v96, v110
	v_mul_f32_e32 v79, v97, v110
	s_waitcnt vmcnt(3)
	v_mov_b32_e32 v81, v240
	v_mov_b32_e32 v83, v241
	v_mov_b32_e32 v85, v242
	v_mov_b32_e32 v87, v243
	v_pk_mul_f32 v[68:69], v[72:73], v[80:81]
	v_pk_mul_f32 v[70:71], v[74:75], v[82:83]
	v_pk_mul_f32 v[72:73], v[76:77], v[84:85]
	v_pk_mul_f32 v[74:75], v[78:79], v[86:87]
	v_mul_f32_e32 v68, v68, v69
	v_mul_f32_e32 v69, v70, v71
	v_mul_f32_e32 v70, v72, v73
	v_mul_f32_e32 v71, v74, v75
	v_cvt_pk_bf16_f32 v68, v68, v69
	v_cvt_pk_bf16_f32 v69, v70, v71
	global_store_dwordx2 v[66:67], v[68:69], off offset:224
	s_waitcnt lgkmcnt(0)
	s_barrier
	s_cbranch_vccz .LBB0_393
